# MLA attention softmax hand-scheduled (fused DPP max, paired bf16 P writes); P2 K-loop scalar bookkeeping moved under MFMA blocks
# speedup vs baseline: 1.0508x; 1.0127x over previous
; __device__ __forceinline__ int fresh_tid() { int t = threadIdx.x; asm volatile("" : "+v"(t)); return t; }
; #define PG8_STAGE(bufoff, gbase) PG8_STAGE_(bufoff, gbase, voffA)
; #define PG8_LDA(dst, b, h) do { _Pragma("unroll") for (int m = 0; m < 4; ++m) _Pragma("unroll") for (int k = 0; k < 2; ++k) dst[m][k] = *(const LAS bf16x8*)(lds + PG8_SA(b, h) + aoff + m * 2048 + k * 1024); } while (0)
; #define PG8_LDB(dst, b, h) do { _Pragma("unroll") for (int n = 0; n < 2; ++n) _Pragma("unroll") for (int k = 0; k < 2; ++k) dst[n][k] = *(const LAS bf16x8*)(lds + PG8_SB(b, h) + boff + n * 2048 + k * 1024); } while (0)
; #define PG8_WAIT_L(n) asm volatile("s_waitcnt lgkmcnt(" #n ")" ::: "memory")
; #define PG8_BAR __builtin_amdgcn_s_barrier()
; #define PG8_SCHED __builtin_amdgcn_sched_barrier(0)
; template <class Epi>
; __device__ __forceinline__ void gemm_phase(LAS unsigned char* lds, const Gemm g, const StaticOrder& S, const Epi& E) {
;     ...
;     for (;;) {
;         const bool has_next = S.next(ui + 1, nxt);
;         const char* nA = has_next ? (const char*)g.A + (size_t)nxt.pm * tstep : cA; const char* nB = has_next ? (const char*)g.Bt + (size_t)nxt.pn * tstep : cB;
;         for (int t = 0; t < nt; t += 2) {
;             const bool last = (t == nt - 2);
;             const char* a1 = cA + (size_t)(t + 1) * kstep;
;             const char* a2 = last ? nA : cA + (size_t)(t + 2) * kstep; const char* b2 = last ? nB : cB + (size_t)(t + 2) * kstep;
;             const char* a3 = a2 + kstep; const char* b3 = b2 + kstep;
;             if constexpr (Epi::RESCALE) { if (t != 0 && (t & 7) == 0) { const int t2 = fresh_tid(); const int w2 = __builtin_amdgcn_readfirstlane(t2 >> 6); E.rescale(acc, cur, t >> 3, w2 >> 2, w2 & 3, t2 & 15, (t2 >> 4) & 3); } }
;             PG8_LDB(B0, 0, 0); PG8_SCHED; PG8_LDA(At, 0, 0); PG8_STAGE(PG8_SA(1, 1), a1 + hstep);
;             PG8_WAIT_L(8); PG8_BAR; PG8_WAIT_L(0); PG8_MMA(0, 0, At, B0); PG8_BAR; PG8_SCHED;
;     ...
;         for (int a = 0; a < 2; ++a)
; #pragma unroll
;             for (int b = 0; b < 2; ++b)
; #pragma unroll
;                 for (int m = 0; m < 4; ++m)
; #pragma unroll
;                     for (int n = 0; n < 2; ++n) acc[a][b][m][n] = (f32x4){0.f, 0.f, 0.f, 0.f};
.LBB0_425:
	v_mov_b64_e32 v[2:3], 0x8a0
	s_ashr_i32 s35, s34, 31
	v_cmp_lt_i64_e32 vcc, s[44:45], v[2:3]
	s_lshl_b64 s[44:45], s[34:35], 20
	s_add_u32 s46, s51, s44
	s_addc_u32 s47, s52, s45
	s_and_b64 s[44:45], vcc, exec
	s_cselect_b32 s35, s47, s31
	s_cselect_b32 s84, s46, s30
	s_ashr_i32 s25, s24, 31
	s_lshl_b64 s[44:45], s[24:25], 20
	s_add_u32 s48, s53, s44
	s_addc_u32 s49, s54, s45
	s_and_b64 s[44:45], vcc, exec
	s_cselect_b32 s25, s49, s21
	s_cselect_b32 s85, s48, s20
	s_add_u32 s30, s30, 0x80080
	s_addc_u32 s31, s31, 0
	s_add_u32 s86, s20, 0x100
	v_mov_b32_e32 v2, 0
	s_addc_u32 s87, s21, 0
	s_mov_b32 s88, -2
	v_mov_b32_e32 v3, v2
	v_mov_b32_e32 v4, v2
	v_mov_b32_e32 v5, v2
	v_mov_b32_e32 v6, v2
	v_mov_b32_e32 v7, v2
	v_mov_b32_e32 v8, v2
	v_mov_b32_e32 v9, v2
	v_mov_b32_e32 v22, v2
	v_mov_b32_e32 v23, v2
	v_mov_b32_e32 v24, v2
	v_mov_b32_e32 v25, v2
	v_mov_b32_e32 v18, v2
	v_mov_b32_e32 v19, v2
	v_mov_b32_e32 v20, v2
	v_mov_b32_e32 v21, v2
	v_mov_b32_e32 v38, v2
	v_mov_b32_e32 v39, v2
	v_mov_b32_e32 v40, v2
	v_mov_b32_e32 v41, v2
	v_mov_b32_e32 v34, v2
	v_mov_b32_e32 v35, v2
	v_mov_b32_e32 v36, v2
	v_mov_b32_e32 v37, v2
	s_waitcnt vmcnt(0)
	v_mov_b32_e32 v54, v2
	v_mov_b32_e32 v55, v2
	v_mov_b32_e32 v56, v2
	v_mov_b32_e32 v57, v2
	v_mov_b32_e32 v50, v2
	v_mov_b32_e32 v51, v2
	v_mov_b32_e32 v52, v2
	v_mov_b32_e32 v53, v2
	v_mov_b32_e32 v14, v2
	v_mov_b32_e32 v15, v2
	v_mov_b32_e32 v16, v2
	v_mov_b32_e32 v17, v2
	v_mov_b32_e32 v10, v2
	v_mov_b32_e32 v11, v2
	v_mov_b32_e32 v12, v2
	v_mov_b32_e32 v13, v2
	v_mov_b32_e32 v30, v2
	v_mov_b32_e32 v31, v2
	v_mov_b32_e32 v32, v2
	v_mov_b32_e32 v33, v2
	v_mov_b32_e32 v26, v2
	v_mov_b32_e32 v27, v2
	v_mov_b32_e32 v28, v2
	v_mov_b32_e32 v29, v2
	v_mov_b32_e32 v46, v2
	v_mov_b32_e32 v47, v2
	v_mov_b32_e32 v48, v2
	v_mov_b32_e32 v49, v2
	v_mov_b32_e32 v42, v2
	v_mov_b32_e32 v43, v2
	v_mov_b32_e32 v44, v2
	v_mov_b32_e32 v45, v2
	v_mov_b32_e32 v62, v2
	v_mov_b32_e32 v63, v2
	v_mov_b32_e32 v64, v2
	v_mov_b32_e32 v65, v2
	v_mov_b32_e32 v58, v2
	v_mov_b32_e32 v59, v2
	v_mov_b32_e32 v60, v2
	v_mov_b32_e32 v61, v2
	v_mov_b32_e32 v70, v2
	v_mov_b32_e32 v71, v2
	v_mov_b32_e32 v72, v2
	v_mov_b32_e32 v73, v2
	v_mov_b32_e32 v66, v2
	v_mov_b32_e32 v67, v2
	v_mov_b32_e32 v68, v2
	v_mov_b32_e32 v69, v2
	v_mov_b32_e32 v102, v2
	v_mov_b32_e32 v103, v2
	v_mov_b32_e32 v104, v2
	v_mov_b32_e32 v105, v2
	v_mov_b32_e32 v98, v2
	v_mov_b32_e32 v99, v2
	v_mov_b32_e32 v100, v2
	v_mov_b32_e32 v101, v2
	v_mov_b32_e32 v118, v2
	v_mov_b32_e32 v119, v2
	v_mov_b32_e32 v120, v2
	v_mov_b32_e32 v121, v2
	v_mov_b32_e32 v114, v2
	v_mov_b32_e32 v115, v2
	v_mov_b32_e32 v116, v2
	v_mov_b32_e32 v117, v2
	v_mov_b32_e32 v134, v2
	v_mov_b32_e32 v135, v2
	v_mov_b32_e32 v136, v2
	v_mov_b32_e32 v137, v2
	v_mov_b32_e32 v130, v2
	v_mov_b32_e32 v131, v2
	v_mov_b32_e32 v132, v2
	v_mov_b32_e32 v133, v2
	v_mov_b32_e32 v82, v2
	v_mov_b32_e32 v83, v2
	v_mov_b32_e32 v84, v2
	v_mov_b32_e32 v85, v2
	v_mov_b32_e32 v78, v2
	v_mov_b32_e32 v79, v2
	v_mov_b32_e32 v80, v2
	v_mov_b32_e32 v81, v2
	v_mov_b32_e32 v110, v2
	v_mov_b32_e32 v111, v2
	v_mov_b32_e32 v112, v2
	v_mov_b32_e32 v113, v2
	v_mov_b32_e32 v106, v2
	v_mov_b32_e32 v107, v2
	v_mov_b32_e32 v108, v2
	v_mov_b32_e32 v109, v2
	v_mov_b32_e32 v126, v2
	v_mov_b32_e32 v127, v2
	v_mov_b32_e32 v128, v2
	v_mov_b32_e32 v129, v2
	v_mov_b32_e32 v122, v2
	v_mov_b32_e32 v123, v2
	v_mov_b32_e32 v124, v2
	v_mov_b32_e32 v125, v2
	v_mov_b32_e32 v142, v2
	v_mov_b32_e32 v143, v2
	v_mov_b32_e32 v144, v2
	v_mov_b32_e32 v145, v2
	v_mov_b32_e32 v138, v2
	v_mov_b32_e32 v139, v2
	v_mov_b32_e32 v140, v2
	v_mov_b32_e32 v141, v2
	v_add_u32_e32 v148, 0x10000, v170
	v_add_u32_e32 v149, 0x14000, v170
	v_add_u32_e32 v150, 0x18000, v170
	v_add_u32_e32 v151, 0x1c000, v170
	s_add_u32 s20, s30, 0xfff80080
	s_addc_u32 s21, s31, -1
	s_add_i32 s58, 0, 0x10000
	s_cmp_eq_u32 s88, 28
	s_cselect_b32 s45, s35, s21
	s_cselect_b32 s44, s84, s20
	s_cselect_b32 s21, s25, s87
	s_cselect_b32 s20, s85, s86
	s_add_u32 s100, s44, s16
	s_addc_u32 s101, s45, s17
	s_add_i32 m0, s62, 0xc000
.LBB0_426:
	ds_read_b128 v[74:77], v148
	ds_read_b128 v[86:89], v148 offset:1024
	ds_read_b128 v[90:93], v148 offset:2048
	ds_read_b128 v[94:97], v148 offset:3072
	ds_read_b128 v[166:169], v171
	ds_read_b128 v[172:175], v171 offset:1024
	ds_read_b128 v[176:179], v171 offset:2048
	ds_read_b128 v[206:209], v171 offset:3072
	ds_read_b128 v[210:213], v171 offset:4096
	ds_read_b128 v[214:217], v171 offset:5120
	ds_read_b128 v[218:221], v171 offset:6144
	global_load_lds_dwordx4 v162, s[30:31]
	s_add_i32 m0, s62, 0xe000
	ds_read_b128 v[222:225], v171 offset:7168
	global_load_lds_dwordx4 v164, s[30:31]
	s_waitcnt lgkmcnt(8)
	s_barrier
	s_waitcnt lgkmcnt(0)
	s_setprio 1
	s_waitcnt lgkmcnt(0)
	v_mfma_f32_16x16x32_bf16 v[138:141], v[74:77], v[166:169], v[138:141]
	v_mfma_f32_16x16x32_bf16 v[142:145], v[90:93], v[166:169], v[142:145]
	s_add_i32 s59, 0, 0x14000
	v_mfma_f32_16x16x32_bf16 v[122:125], v[74:77], v[176:179], v[122:125]
	s_add_i32 s58, s58, s55
	v_mfma_f32_16x16x32_bf16 v[126:129], v[90:93], v[176:179], v[126:129]
	s_mov_b32 m0, s58
	v_mfma_f32_16x16x32_bf16 v[106:109], v[74:77], v[210:213], v[106:109]
	v_mfma_f32_16x16x32_bf16 v[110:113], v[90:93], v[210:213], v[110:113]
	v_mfma_f32_16x16x32_bf16 v[78:81], v[74:77], v[218:221], v[78:81]
	v_mfma_f32_16x16x32_bf16 v[82:85], v[90:93], v[218:221], v[82:85]
	v_mfma_f32_16x16x32_bf16 v[138:141], v[86:89], v[172:175], v[138:141]
	v_mfma_f32_16x16x32_bf16 v[142:145], v[94:97], v[172:175], v[142:145]
	v_mfma_f32_16x16x32_bf16 v[122:125], v[86:89], v[206:209], v[122:125]
	v_mfma_f32_16x16x32_bf16 v[126:129], v[94:97], v[206:209], v[126:129]
	v_mfma_f32_16x16x32_bf16 v[106:109], v[86:89], v[214:217], v[106:109]
	v_mfma_f32_16x16x32_bf16 v[110:113], v[94:97], v[214:217], v[110:113]
	v_mfma_f32_16x16x32_bf16 v[78:81], v[86:89], v[222:225], v[78:81]
	v_mfma_f32_16x16x32_bf16 v[82:85], v[94:97], v[222:225], v[82:85]
	s_setprio 0
	s_barrier
; #define PG8_STAGE(bufoff, gbase) PG8_STAGE_(bufoff, gbase, voffA)
; #define PG8_STAGEB(bufoff, gbase) PG8_STAGE_(bufoff, gbase, voffB)
; #define PG8_LDA(dst, b, h) do { _Pragma("unroll") for (int m = 0; m < 4; ++m) _Pragma("unroll") for (int k = 0; k < 2; ++k) dst[m][k] = *(const LAS bf16x8*)(lds + PG8_SA(b, h) + aoff + m * 2048 + k * 1024); } while (0)
; #define PG8_LDB(dst, b, h) do { _Pragma("unroll") for (int n = 0; n < 2; ++n) _Pragma("unroll") for (int k = 0; k < 2; ++k) dst[n][k] = *(const LAS bf16x8*)(lds + PG8_SB(b, h) + boff + n * 2048 + k * 1024); } while (0)
; #define PG8_MMA(ai, bj, At, Bt) do { __builtin_amdgcn_s_setprio(1); _Pragma("unroll") for (int m = 0; m < 4; ++m) _Pragma("unroll") for (int n = 0; n < 2; ++n) _Pragma("unroll") for (int k = 0; k < 2; ++k) \
;         acc[ai][bj][m][n] = __builtin_amdgcn_mfma_f32_16x16x32_bf16(Bt[n][k], At[m][k], acc[ai][bj][m][n], 0, 0, 0); __builtin_amdgcn_s_setprio(0); } while (0)
; #define PG8_WAIT_V(n) asm volatile("s_waitcnt vmcnt(" #n ")" ::: "memory")
; #define PG8_WAIT_L(n) asm volatile("s_waitcnt lgkmcnt(" #n ")" ::: "memory")
; #define PG8_BAR __builtin_amdgcn_s_barrier()
; #define PG8_SCHED __builtin_amdgcn_sched_barrier(0)
; template <class Epi>
; __device__ __forceinline__ void gemm_phase(LAS unsigned char* lds, const Gemm g, const StaticOrder& S, const Epi& E) {
;     ...
;             PG8_LDB(B1, 0, 1); PG8_STAGEB(PG8_SB(0, 0), b2);
;             PG8_BAR; PG8_WAIT_L(0); PG8_MMA(0, 1, At, B1); PG8_BAR;
;             PG8_LDA(At, 0, 1); PG8_STAGE(PG8_SA(0, 0), a2);
;             PG8_BAR; PG8_WAIT_L(0); PG8_MMA(1, 0, At, B0); PG8_BAR; PG8_SCHED;
;             PG8_STAGEB(PG8_SB(0, 1), b2 + hstep);
;             PG8_WAIT_V(6); PG8_BAR; PG8_MMA(1, 1, At, B1); PG8_BAR;
;             PG8_LDB(B0, 1, 0); PG8_SCHED; PG8_LDA(At, 1, 0); PG8_STAGE(PG8_SA(0, 1), a2 + hstep);
;             PG8_WAIT_L(8); PG8_BAR; PG8_WAIT_L(0); PG8_MMA(0, 0, At, B0); PG8_BAR; PG8_SCHED;
;             PG8_LDB(B1, 1, 1); PG8_STAGEB(PG8_SB(1, 0), b3);
	ds_read_b128 v[226:229], v149
	ds_read_b128 v[230:233], v149 offset:1024
	ds_read_b128 v[234:237], v149 offset:2048
	global_load_lds_dwordx4 v0, s[20:21]
	s_add_i32 m0, s58, 0x2000
	ds_read_b128 v[238:241], v149 offset:3072
	global_load_lds_dwordx4 v156, s[20:21]
	s_barrier
	s_waitcnt lgkmcnt(0)
	s_setprio 1
	s_waitcnt lgkmcnt(0)
	v_mfma_f32_16x16x32_bf16 v[130:133], v[226:229], v[166:169], v[130:133]
	v_mfma_f32_16x16x32_bf16 v[134:137], v[234:237], v[166:169], v[134:137]
	v_mfma_f32_16x16x32_bf16 v[114:117], v[226:229], v[176:179], v[114:117]
	v_mfma_f32_16x16x32_bf16 v[118:121], v[234:237], v[176:179], v[118:121]
	v_mfma_f32_16x16x32_bf16 v[98:101], v[226:229], v[210:213], v[98:101]
	v_mfma_f32_16x16x32_bf16 v[102:105], v[234:237], v[210:213], v[102:105]
	v_mfma_f32_16x16x32_bf16 v[66:69], v[226:229], v[218:221], v[66:69]
	v_mfma_f32_16x16x32_bf16 v[70:73], v[234:237], v[218:221], v[70:73]
	v_mfma_f32_16x16x32_bf16 v[130:133], v[230:233], v[172:175], v[130:133]
	v_mfma_f32_16x16x32_bf16 v[134:137], v[238:241], v[172:175], v[134:137]
	v_mfma_f32_16x16x32_bf16 v[114:117], v[230:233], v[206:209], v[114:117]
	v_mfma_f32_16x16x32_bf16 v[118:121], v[238:241], v[206:209], v[118:121]
	v_mfma_f32_16x16x32_bf16 v[98:101], v[230:233], v[214:217], v[98:101]
	v_mfma_f32_16x16x32_bf16 v[102:105], v[238:241], v[214:217], v[102:105]
	v_mfma_f32_16x16x32_bf16 v[66:69], v[230:233], v[222:225], v[66:69]
	v_mfma_f32_16x16x32_bf16 v[70:73], v[238:241], v[222:225], v[70:73]
	s_setprio 0
	s_mov_b32 m0, s62
	s_barrier
	ds_read_b128 v[166:169], v171 offset:16384
	ds_read_b128 v[172:175], v171 offset:17408
	ds_read_b128 v[176:179], v171 offset:18432
	ds_read_b128 v[206:209], v171 offset:19456
	ds_read_b128 v[210:213], v171 offset:20480
	ds_read_b128 v[214:217], v171 offset:21504
	ds_read_b128 v[218:221], v171 offset:22528
	global_load_lds_dwordx4 v160, s[44:45]
	s_mov_b32 m0, s63
	ds_read_b128 v[222:225], v171 offset:23552
	global_load_lds_dwordx4 v158, s[44:45]
	s_barrier
	s_waitcnt lgkmcnt(0)
	s_setprio 1
	s_waitcnt lgkmcnt(0)
	v_mfma_f32_16x16x32_bf16 v[58:61], v[74:77], v[166:169], v[58:61]
	v_mfma_f32_16x16x32_bf16 v[62:65], v[90:93], v[166:169], v[62:65]
	s_add_u32 s90, s20, 0x80000
	v_mfma_f32_16x16x32_bf16 v[42:45], v[74:77], v[176:179], v[42:45]
	s_addc_u32 s91, s21, 0
	v_mfma_f32_16x16x32_bf16 v[46:49], v[90:93], v[176:179], v[46:49]
	s_add_i32 s58, s59, s55
	v_mfma_f32_16x16x32_bf16 v[26:29], v[74:77], v[210:213], v[26:29]
	s_mov_b32 m0, s58
	v_mfma_f32_16x16x32_bf16 v[30:33], v[90:93], v[210:213], v[30:33]
	v_mfma_f32_16x16x32_bf16 v[10:13], v[74:77], v[218:221], v[10:13]
	v_mfma_f32_16x16x32_bf16 v[14:17], v[90:93], v[218:221], v[14:17]
	v_mfma_f32_16x16x32_bf16 v[58:61], v[86:89], v[172:175], v[58:61]
	v_mfma_f32_16x16x32_bf16 v[62:65], v[94:97], v[172:175], v[62:65]
	v_mfma_f32_16x16x32_bf16 v[42:45], v[86:89], v[206:209], v[42:45]
	v_mfma_f32_16x16x32_bf16 v[46:49], v[94:97], v[206:209], v[46:49]
	v_mfma_f32_16x16x32_bf16 v[26:29], v[86:89], v[214:217], v[26:29]
	v_mfma_f32_16x16x32_bf16 v[30:33], v[94:97], v[214:217], v[30:33]
	v_mfma_f32_16x16x32_bf16 v[10:13], v[86:89], v[222:225], v[10:13]
	v_mfma_f32_16x16x32_bf16 v[14:17], v[94:97], v[222:225], v[14:17]
	s_setprio 0
	s_barrier
	global_load_lds_dwordx4 v0, s[90:91]
	s_add_i32 m0, s58, 0x2000
	s_nop 0
	global_load_lds_dwordx4 v156, s[90:91]
	s_waitcnt vmcnt(6)
	s_barrier
	s_setprio 1
	v_mfma_f32_16x16x32_bf16 v[50:53], v[226:229], v[166:169], v[50:53]
	v_mfma_f32_16x16x32_bf16 v[54:57], v[234:237], v[166:169], v[54:57]
	s_add_i32 s58, 0, 0x18000
	v_mfma_f32_16x16x32_bf16 v[34:37], v[226:229], v[176:179], v[34:37]
	s_add_u32 s44, s44, 0x80000
	v_mfma_f32_16x16x32_bf16 v[38:41], v[234:237], v[176:179], v[38:41]
	s_addc_u32 s45, s45, 0
	v_mfma_f32_16x16x32_bf16 v[18:21], v[226:229], v[210:213], v[18:21]
	s_mov_b32 m0, s66
	v_mfma_f32_16x16x32_bf16 v[22:25], v[234:237], v[210:213], v[22:25]
	s_add_u32 s90, s20, s16
	v_mfma_f32_16x16x32_bf16 v[6:9], v[226:229], v[218:221], v[6:9]
	s_addc_u32 s91, s21, s17
	v_mfma_f32_16x16x32_bf16 v[2:5], v[234:237], v[218:221], v[2:5]
	v_mfma_f32_16x16x32_bf16 v[50:53], v[230:233], v[172:175], v[50:53]
	v_mfma_f32_16x16x32_bf16 v[54:57], v[238:241], v[172:175], v[54:57]
	v_mfma_f32_16x16x32_bf16 v[34:37], v[230:233], v[206:209], v[34:37]
	v_mfma_f32_16x16x32_bf16 v[38:41], v[238:241], v[206:209], v[38:41]
	v_mfma_f32_16x16x32_bf16 v[18:21], v[230:233], v[214:217], v[18:21]
	v_mfma_f32_16x16x32_bf16 v[22:25], v[238:241], v[214:217], v[22:25]
	v_mfma_f32_16x16x32_bf16 v[6:9], v[230:233], v[222:225], v[6:9]
	v_mfma_f32_16x16x32_bf16 v[2:5], v[238:241], v[222:225], v[2:5]
	s_setprio 0
	s_barrier
	ds_read_b128 v[74:77], v150
	ds_read_b128 v[86:89], v150 offset:1024
	ds_read_b128 v[90:93], v150 offset:2048
	ds_read_b128 v[94:97], v150 offset:3072
	ds_read_b128 v[166:169], v171 offset:32768
	ds_read_b128 v[172:175], v171 offset:33792
	ds_read_b128 v[176:179], v171 offset:34816
	ds_read_b128 v[206:209], v171 offset:35840
	ds_read_b128 v[210:213], v171 offset:36864
	ds_read_b128 v[214:217], v171 offset:37888
	ds_read_b128 v[218:221], v171 offset:38912
	global_load_lds_dwordx4 v160, s[44:45]
	s_mov_b32 m0, s67
	ds_read_b128 v[222:225], v171 offset:39936
	global_load_lds_dwordx4 v158, s[44:45]
	s_waitcnt lgkmcnt(8)
	s_barrier
; #define PG8_STAGE(bufoff, gbase) PG8_STAGE_(bufoff, gbase, voffA)
; #define PG8_STAGEB(bufoff, gbase) PG8_STAGE_(bufoff, gbase, voffB)
; #define PG8_LDA(dst, b, h) do { _Pragma("unroll") for (int m = 0; m < 4; ++m) _Pragma("unroll") for (int k = 0; k < 2; ++k) dst[m][k] = *(const LAS bf16x8*)(lds + PG8_SA(b, h) + aoff + m * 2048 + k * 1024); } while (0)
; #define PG8_LDB(dst, b, h) do { _Pragma("unroll") for (int n = 0; n < 2; ++n) _Pragma("unroll") for (int k = 0; k < 2; ++k) dst[n][k] = *(const LAS bf16x8*)(lds + PG8_SB(b, h) + boff + n * 2048 + k * 1024); } while (0)
; #define PG8_MMA(ai, bj, At, Bt) do { __builtin_amdgcn_s_setprio(1); _Pragma("unroll") for (int m = 0; m < 4; ++m) _Pragma("unroll") for (int n = 0; n < 2; ++n) _Pragma("unroll") for (int k = 0; k < 2; ++k) \
;         acc[ai][bj][m][n] = __builtin_amdgcn_mfma_f32_16x16x32_bf16(Bt[n][k], At[m][k], acc[ai][bj][m][n], 0, 0, 0); __builtin_amdgcn_s_setprio(0); } while (0)
; #define PG8_WAIT_V(n) asm volatile("s_waitcnt vmcnt(" #n ")" ::: "memory")
; #define PG8_WAIT_L(n) asm volatile("s_waitcnt lgkmcnt(" #n ")" ::: "memory")
; #define PG8_BAR __builtin_amdgcn_s_barrier()
; #define PG8_SCHED __builtin_amdgcn_sched_barrier(0)
; template <class Epi>
; __device__ __forceinline__ void gemm_phase(LAS unsigned char* lds, const Gemm g, const StaticOrder& S, const Epi& E) {
;     ...
;             PG8_WAIT_L(8); PG8_BAR; PG8_WAIT_L(0); PG8_MMA(0, 0, At, B0); PG8_BAR; PG8_SCHED;
;             PG8_LDB(B1, 0, 1); PG8_STAGEB(PG8_SB(0, 0), b2);
;             PG8_BAR; PG8_WAIT_L(0); PG8_MMA(0, 1, At, B1); PG8_BAR;
;             PG8_LDA(At, 0, 1); PG8_STAGE(PG8_SA(0, 0), a2);
;             PG8_BAR; PG8_WAIT_L(0); PG8_MMA(1, 0, At, B0); PG8_BAR; PG8_SCHED;
;             PG8_STAGEB(PG8_SB(0, 1), b2 + hstep);
;             PG8_WAIT_V(6); PG8_BAR; PG8_MMA(1, 1, At, B1); PG8_BAR;
;             PG8_LDB(B0, 1, 0); PG8_SCHED; PG8_LDA(At, 1, 0); PG8_STAGE(PG8_SA(0, 1), a2 + hstep);
	s_waitcnt lgkmcnt(0)
	s_setprio 1
	s_waitcnt lgkmcnt(0)
	v_mfma_f32_16x16x32_bf16 v[138:141], v[74:77], v[166:169], v[138:141]
	v_mfma_f32_16x16x32_bf16 v[142:145], v[90:93], v[166:169], v[142:145]
	s_add_i32 s44, 0, 0x1c000
	v_mfma_f32_16x16x32_bf16 v[122:125], v[74:77], v[176:179], v[122:125]
	s_add_i32 s45, s58, s55
	v_mfma_f32_16x16x32_bf16 v[126:129], v[90:93], v[176:179], v[126:129]
	s_mov_b32 m0, s45
	v_mfma_f32_16x16x32_bf16 v[106:109], v[74:77], v[210:213], v[106:109]
	v_mfma_f32_16x16x32_bf16 v[110:113], v[90:93], v[210:213], v[110:113]
	v_mfma_f32_16x16x32_bf16 v[78:81], v[74:77], v[218:221], v[78:81]
	v_mfma_f32_16x16x32_bf16 v[82:85], v[90:93], v[218:221], v[82:85]
	v_mfma_f32_16x16x32_bf16 v[138:141], v[86:89], v[172:175], v[138:141]
	v_mfma_f32_16x16x32_bf16 v[142:145], v[94:97], v[172:175], v[142:145]
	v_mfma_f32_16x16x32_bf16 v[122:125], v[86:89], v[206:209], v[122:125]
	v_mfma_f32_16x16x32_bf16 v[126:129], v[94:97], v[206:209], v[126:129]
	v_mfma_f32_16x16x32_bf16 v[106:109], v[86:89], v[214:217], v[106:109]
	v_mfma_f32_16x16x32_bf16 v[110:113], v[94:97], v[214:217], v[110:113]
	v_mfma_f32_16x16x32_bf16 v[78:81], v[86:89], v[222:225], v[78:81]
	v_mfma_f32_16x16x32_bf16 v[82:85], v[94:97], v[222:225], v[82:85]
	s_setprio 0
	s_barrier
	ds_read_b128 v[226:229], v151
	ds_read_b128 v[230:233], v151 offset:1024
	ds_read_b128 v[234:237], v151 offset:2048
	global_load_lds_dwordx4 v0, s[90:91]
	s_add_i32 m0, s45, 0x2000
	ds_read_b128 v[238:241], v151 offset:3072
	global_load_lds_dwordx4 v156, s[90:91]
	s_barrier
	s_waitcnt lgkmcnt(0)
	s_setprio 1
	s_waitcnt lgkmcnt(0)
	v_mfma_f32_16x16x32_bf16 v[130:133], v[226:229], v[166:169], v[130:133]
	v_mfma_f32_16x16x32_bf16 v[134:137], v[234:237], v[166:169], v[134:137]
	v_mfma_f32_16x16x32_bf16 v[114:117], v[226:229], v[176:179], v[114:117]
	v_mfma_f32_16x16x32_bf16 v[118:121], v[234:237], v[176:179], v[118:121]
	v_mfma_f32_16x16x32_bf16 v[98:101], v[226:229], v[210:213], v[98:101]
	v_mfma_f32_16x16x32_bf16 v[102:105], v[234:237], v[210:213], v[102:105]
	v_mfma_f32_16x16x32_bf16 v[66:69], v[226:229], v[218:221], v[66:69]
	v_mfma_f32_16x16x32_bf16 v[70:73], v[234:237], v[218:221], v[70:73]
	v_mfma_f32_16x16x32_bf16 v[130:133], v[230:233], v[172:175], v[130:133]
	v_mfma_f32_16x16x32_bf16 v[134:137], v[238:241], v[172:175], v[134:137]
	v_mfma_f32_16x16x32_bf16 v[114:117], v[230:233], v[206:209], v[114:117]
	v_mfma_f32_16x16x32_bf16 v[118:121], v[238:241], v[206:209], v[118:121]
	v_mfma_f32_16x16x32_bf16 v[98:101], v[230:233], v[214:217], v[98:101]
	v_mfma_f32_16x16x32_bf16 v[102:105], v[238:241], v[214:217], v[102:105]
	v_mfma_f32_16x16x32_bf16 v[66:69], v[230:233], v[222:225], v[66:69]
	v_mfma_f32_16x16x32_bf16 v[70:73], v[238:241], v[222:225], v[70:73]
	s_setprio 0
	s_mov_b32 m0, s38
	s_barrier
	ds_read_b128 v[166:169], v171 offset:49152
	ds_read_b128 v[172:175], v171 offset:50176
	ds_read_b128 v[176:179], v171 offset:51200
	ds_read_b128 v[206:209], v171 offset:52224
	ds_read_b128 v[210:213], v171 offset:53248
	ds_read_b128 v[214:217], v171 offset:54272
	ds_read_b128 v[218:221], v171 offset:55296
	global_load_lds_dwordx4 v160, s[100:101]
	s_mov_b32 m0, s80
	ds_read_b128 v[222:225], v171 offset:56320
	global_load_lds_dwordx4 v158, s[100:101]
	s_barrier
; #define PG8_STAGE(bufoff, gbase) PG8_STAGE_(bufoff, gbase, voffA)
; #define PG8_STAGEB(bufoff, gbase) PG8_STAGE_(bufoff, gbase, voffB)
; #define PG8_LDA(dst, b, h) do { _Pragma("unroll") for (int m = 0; m < 4; ++m) _Pragma("unroll") for (int k = 0; k < 2; ++k) dst[m][k] = *(const LAS bf16x8*)(lds + PG8_SA(b, h) + aoff + m * 2048 + k * 1024); } while (0)
; #define PG8_LDB(dst, b, h) do { _Pragma("unroll") for (int n = 0; n < 2; ++n) _Pragma("unroll") for (int k = 0; k < 2; ++k) dst[n][k] = *(const LAS bf16x8*)(lds + PG8_SB(b, h) + boff + n * 2048 + k * 1024); } while (0)
; #define PG8_MMA(ai, bj, At, Bt) do { __builtin_amdgcn_s_setprio(1); _Pragma("unroll") for (int m = 0; m < 4; ++m) _Pragma("unroll") for (int n = 0; n < 2; ++n) _Pragma("unroll") for (int k = 0; k < 2; ++k) \
;         acc[ai][bj][m][n] = __builtin_amdgcn_mfma_f32_16x16x32_bf16(Bt[n][k], At[m][k], acc[ai][bj][m][n], 0, 0, 0); __builtin_amdgcn_s_setprio(0); } while (0)
; #define PG8_WAIT_V(n) asm volatile("s_waitcnt vmcnt(" #n ")" ::: "memory")
; template <class Epi>
; __device__ __forceinline__ void gemm_phase(LAS unsigned char* lds, const Gemm g, const StaticOrder& S, const Epi& E) {
;     ...
;             PG8_WAIT_V(6); PG8_BAR; PG8_MMA(1, 1, At, B1); PG8_BAR;
;             PG8_LDB(B0, 1, 0); PG8_SCHED; PG8_LDA(At, 1, 0); PG8_STAGE(PG8_SA(0, 1), a2 + hstep);
;             PG8_WAIT_L(8); PG8_BAR; PG8_WAIT_L(0); PG8_MMA(0, 0, At, B0); PG8_BAR; PG8_SCHED;
;             PG8_LDB(B1, 1, 1); PG8_STAGEB(PG8_SB(1, 0), b3);
;             PG8_BAR; PG8_WAIT_L(0); PG8_MMA(0, 1, At, B1); PG8_BAR;
;             PG8_LDA(At, 1, 1); PG8_STAGE(PG8_SA(1, 0), a3);
;             PG8_BAR; PG8_WAIT_L(0); PG8_MMA(1, 0, At, B0); PG8_BAR; PG8_SCHED;
;             PG8_STAGEB(PG8_SB(1, 1), b3 + hstep);
;             PG8_WAIT_V(6); PG8_BAR; PG8_MMA(1, 1, At, B1); PG8_BAR;
;     __device__ __forceinline__ void operator()(AccT& acc, const Unit& u, int wr, int wc, int fr, int fq) const {
;         int row0 = u.pm * 256 + wr * 64 + fr, col0 = u.pn * 256 + wc * 32 + 8 * fq;
;         asm volatile("" : "+v"(row0), "+v"(col0));
;         const bool gate = u.pn >= 37;
;         f32x4 bv[2][2];
; #pragma unroll
;         for (int bj = 0; bj < 2; ++bj)
; #pragma unroll
;             for (int n = 0; n < 2; ++n) bv[bj][n] = gate ? *(const f32x4*)(mb + (col0 - GATE0) + bj * 128 + n * 4) : (f32x4){0.f, 0.f, 0.f, 0.f};
	s_waitcnt lgkmcnt(0)
	s_setprio 1
	s_waitcnt lgkmcnt(0)
	v_mfma_f32_16x16x32_bf16 v[58:61], v[74:77], v[166:169], v[58:61]
	v_mfma_f32_16x16x32_bf16 v[62:65], v[90:93], v[166:169], v[62:65]
	s_add_u32 s20, s20, 0x80080
	v_mfma_f32_16x16x32_bf16 v[42:45], v[74:77], v[176:179], v[42:45]
	s_addc_u32 s21, s21, 0
	v_mfma_f32_16x16x32_bf16 v[46:49], v[90:93], v[176:179], v[46:49]
	s_add_i32 s44, s44, s55
	v_mfma_f32_16x16x32_bf16 v[26:29], v[74:77], v[210:213], v[26:29]
	s_mov_b32 m0, s44
	v_mfma_f32_16x16x32_bf16 v[30:33], v[90:93], v[210:213], v[30:33]
	v_mfma_f32_16x16x32_bf16 v[10:13], v[74:77], v[218:221], v[10:13]
	v_mfma_f32_16x16x32_bf16 v[14:17], v[90:93], v[218:221], v[14:17]
	v_mfma_f32_16x16x32_bf16 v[58:61], v[86:89], v[172:175], v[58:61]
	v_mfma_f32_16x16x32_bf16 v[62:65], v[94:97], v[172:175], v[62:65]
	v_mfma_f32_16x16x32_bf16 v[42:45], v[86:89], v[206:209], v[42:45]
	v_mfma_f32_16x16x32_bf16 v[46:49], v[94:97], v[206:209], v[46:49]
	v_mfma_f32_16x16x32_bf16 v[26:29], v[86:89], v[214:217], v[26:29]
	v_mfma_f32_16x16x32_bf16 v[30:33], v[94:97], v[214:217], v[30:33]
	v_mfma_f32_16x16x32_bf16 v[10:13], v[86:89], v[222:225], v[10:13]
	v_mfma_f32_16x16x32_bf16 v[14:17], v[94:97], v[222:225], v[14:17]
	s_setprio 0
	s_barrier
	global_load_lds_dwordx4 v0, s[20:21]
	s_add_i32 m0, s44, 0x2000
	s_nop 0
	global_load_lds_dwordx4 v156, s[20:21]
	s_waitcnt vmcnt(6)
	s_barrier
	s_setprio 1
	v_mfma_f32_16x16x32_bf16 v[50:53], v[226:229], v[166:169], v[50:53]
	v_mfma_f32_16x16x32_bf16 v[54:57], v[234:237], v[166:169], v[54:57]
	s_add_i32 s88, s88, 2
	v_mfma_f32_16x16x32_bf16 v[34:37], v[226:229], v[176:179], v[34:37]
	s_add_u32 s30, s30, 0x100
	v_mfma_f32_16x16x32_bf16 v[38:41], v[234:237], v[176:179], v[38:41]
	s_addc_u32 s31, s31, 0
	v_mfma_f32_16x16x32_bf16 v[18:21], v[226:229], v[210:213], v[18:21]
	s_add_u32 s86, s86, 0x100
	v_mfma_f32_16x16x32_bf16 v[22:25], v[234:237], v[210:213], v[22:25]
	s_addc_u32 s87, s87, 0
	v_mfma_f32_16x16x32_bf16 v[6:9], v[226:229], v[218:221], v[6:9]
	s_add_u32 s20, s30, 0xfff80080
	v_mfma_f32_16x16x32_bf16 v[2:5], v[234:237], v[218:221], v[2:5]
	s_addc_u32 s21, s31, -1
	v_mfma_f32_16x16x32_bf16 v[50:53], v[230:233], v[172:175], v[50:53]
	s_add_i32 s58, 0, 0x10000
	v_mfma_f32_16x16x32_bf16 v[54:57], v[238:241], v[172:175], v[54:57]
	s_cmp_eq_u32 s88, 28
	v_mfma_f32_16x16x32_bf16 v[34:37], v[230:233], v[206:209], v[34:37]
	s_cselect_b32 s45, s35, s21
	v_mfma_f32_16x16x32_bf16 v[38:41], v[238:241], v[206:209], v[38:41]
	s_cselect_b32 s44, s84, s20
	v_mfma_f32_16x16x32_bf16 v[18:21], v[230:233], v[214:217], v[18:21]
	s_cselect_b32 s21, s25, s87
	v_mfma_f32_16x16x32_bf16 v[22:25], v[238:241], v[214:217], v[22:25]
	s_cselect_b32 s20, s85, s86
	v_mfma_f32_16x16x32_bf16 v[6:9], v[230:233], v[222:225], v[6:9]
	s_add_u32 s100, s44, s16
	v_mfma_f32_16x16x32_bf16 v[2:5], v[238:241], v[222:225], v[2:5]
	s_addc_u32 s101, s45, s17
	s_add_i32 m0, s62, 0xc000
	s_setprio 0
	s_cmp_gt_u32 s88, 29
	s_barrier
	s_cbranch_scc0 .LBB0_426
	v_mov_b32_e32 v74, v250
	s_lshl_b32 s21, s83, 8
	v_readfirstlane_b32 s20, v74
	s_ashr_i32 s25, s20, 2
	s_andn2_b32 s25, s25, 63
	s_lshr_b32 s20, s20, 1
	s_add_i32 s25, s25, s21
	s_lshl_b32 s21, s82, 8
	s_and_b32 s20, s20, 0x60
	v_and_or_b32 v172, v74, 15, s25
	s_or_b32 s20, s20, s21
	v_lshrrev_b32_e32 v74, 1, v74
	v_and_or_b32 v166, v74, 24, s20
	s_cmp_gt_i32 s82, 36
	v_ashrrev_i32_e32 v167, 31, v166
	v_mov_b32_e32 v90, 0
	s_cselect_b64 s[20:21], -1, 0
	s_cmp_lt_i32 s82, 37
	v_lshl_add_u64 v[168:169], v[166:167], 2, s[6:7]
	v_mov_b32_e32 v94, 0
	v_mov_b32_e32 v95, v90
	v_mov_b32_e32 v96, 0
	v_mov_b32_e32 v97, 0
	s_cbranch_scc1 .LBB0_429
	v_add_co_u32_e32 v74, vcc, 0xffff7000, v168
	s_nop 1
	v_addc_co_u32_e32 v75, vcc, -1, v169, vcc
	global_load_dwordx4 v[94:97], v[74:75], off offset:-1024

; #define LAS __attribute__((address_space(3)))
; template <int DQK>
; __device__ __forceinline__ void attn_block(LAS unsigned char* lds, const bf16_t* Qp, const bf16_t* Kp, const bf16_t* VTp, int q_idx0, int kt_lo, int kt_hi,
;                                            int maxdelta, float bslope, int dsh, bf16_t* Op, float* Lp, int head) {
;     ...
; #pragma unroll
;           for (int n = 0; n < 4; ++n) kf[0][n] = *(const LAS bf16x8*)(kbase_p + (n * 16 * KS) * 2);
; #pragma unroll
;           for (int ks = 0; ks < DQK / 32; ++ks) {
;               if (ks + 1 < DQK / 32) {
; #pragma unroll
;                   for (int n = 0; n < 4; ++n) kf[(ks + 1) & 1][n] = *(const LAS bf16x8*)(kbase_p + (n * 16 * KS + (ks + 1) * 32) * 2); }
;               __builtin_amdgcn_sched_barrier(0);
; #pragma unroll
;               for (int n = 0; n < 4; ++n) s[n] = __builtin_amdgcn_mfma_f32_16x16x32_bf16(qf[ks], kf[ks & 1][n], s[n], 0, 0, 0);
;               __builtin_amdgcn_sched_barrier(0);
;           } }
;         if constexpr (decltype(masktag)::value) {
;         const int kbase = kt * 64 + fr;
; #pragma unroll
;         for (int j = 0; j < 4; ++j) {
;             const int qi = q_idx0 + wave * 16 + fq * 4 + j;
;             float tmax = -1e30f;
; #pragma unroll
;             for (int n = 0; n < 4; ++n) { const int delta = qi - (kbase + n * 16); const bool valid = (unsigned)delta <= (unsigned)maxdelta;
;                 const float sv = valid ? s[n][j] - bslope * (float)delta : -1e30f; s[n][j] = sv; tmax = fmaxf(tmax, sv); }
;             tmax = row16_max(tmax);
;             const float mn = fmaxf(m_run[j], tmax), alpha = __builtin_amdgcn_exp2f(m_run[j] - mn);
;             m_run[j] = mn;
;             float psum = 0.f;
; #pragma unroll
;             for (int n = 0; n < 4; ++n) { const float p = s[n][j] > -1e29f ? __builtin_amdgcn_exp2f(s[n][j] - mn) : 0.f; psum += p;
;                 *(LAS bf16_t*)(Pw + ((fq * 4 + j) * 72 + n * 16 + fr) * 2) = f2bf(p); }
;             l_run[j] = l_run[j] * alpha + psum;
; #pragma unroll
;             for (int d = 0; d < 8; ++d) o[d][j] *= alpha;
;         }
;         } else {
;             float mn[4];
; #pragma unroll
;             for (int j = 0; j < 4; ++j) { float tmax = fmaxf(fmaxf(s[0][j], s[1][j]), fmaxf(s[2][j], s[3][j])); tmax = row16_max(tmax); mn[j] = fmaxf(m_run[j], tmax); }
; #pragma unroll
.LBB0_1218:
	s_and_b32 s21, s21, 1
	s_mul_i32 s31, s21, 0x6400
	v_add_u32_e32 v128, s31, v0
	ds_read_b128 v[78:81], v128
	ds_read_b128 v[82:85], v128 offset:64
	ds_read_b128 v[86:89], v128 offset:6400
	ds_read_b128 v[90:93], v128 offset:6464
	ds_read_b128 v[146:149], v128 offset:12800
	ds_read_b128 v[150:153], v128 offset:12864
	ds_read_b128 v[168:171], v128 offset:19200
	ds_read_b128 v[172:175], v128 offset:19264
	s_waitcnt lgkmcnt(7)
	v_mfma_f32_16x16x32_bf16 v[78:81], v[14:17], v[78:81], 0
	s_waitcnt lgkmcnt(5)
	v_mfma_f32_16x16x32_bf16 v[86:89], v[14:17], v[86:89], 0
	s_waitcnt lgkmcnt(3)
	v_mfma_f32_16x16x32_bf16 v[146:149], v[14:17], v[146:149], 0
	s_waitcnt lgkmcnt(1)
	v_mfma_f32_16x16x32_bf16 v[168:171], v[14:17], v[168:171], 0
	ds_read_b128 v[176:179], v128 offset:128
	ds_read_b128 v[188:191], v128 offset:6528
	ds_read_b128 v[192:195], v128 offset:12928
	ds_read_b128 v[196:199], v128 offset:19328
	v_mfma_f32_16x16x32_bf16 v[78:81], v[22:25], v[82:85], v[78:81]
	v_mfma_f32_16x16x32_bf16 v[82:85], v[22:25], v[90:93], v[86:89]
	v_mfma_f32_16x16x32_bf16 v[86:89], v[22:25], v[150:153], v[146:149]
	s_waitcnt lgkmcnt(4)
	v_mfma_f32_16x16x32_bf16 v[90:93], v[22:25], v[172:175], v[168:171]
	s_nop 0
	ds_read_b128 v[146:149], v128 offset:192
	ds_read_b128 v[150:153], v128 offset:6592
	ds_read_b128 v[168:171], v128 offset:12992
	ds_read_b128 v[172:175], v128 offset:19392
	s_waitcnt lgkmcnt(7)
	v_mfma_f32_16x16x32_bf16 v[78:81], v[26:29], v[176:179], v[78:81]
	s_waitcnt lgkmcnt(6)
	v_mfma_f32_16x16x32_bf16 v[82:85], v[26:29], v[188:191], v[82:85]
	s_waitcnt lgkmcnt(5)
	v_mfma_f32_16x16x32_bf16 v[86:89], v[26:29], v[192:195], v[86:89]
	s_waitcnt lgkmcnt(4)
	v_mfma_f32_16x16x32_bf16 v[90:93], v[26:29], v[196:199], v[90:93]
	ds_read_b128 v[176:179], v128 offset:256
	ds_read_b128 v[188:191], v128 offset:6656
	ds_read_b128 v[192:195], v128 offset:13056
	ds_read_b128 v[196:199], v128 offset:19456
	s_waitcnt lgkmcnt(7)
	v_mfma_f32_16x16x32_bf16 v[78:81], v[30:33], v[146:149], v[78:81]
	s_waitcnt lgkmcnt(6)
	v_mfma_f32_16x16x32_bf16 v[82:85], v[30:33], v[150:153], v[82:85]
	s_waitcnt lgkmcnt(5)
	v_mfma_f32_16x16x32_bf16 v[86:89], v[30:33], v[168:171], v[86:89]
	s_waitcnt lgkmcnt(4)
	v_mfma_f32_16x16x32_bf16 v[90:93], v[30:33], v[172:175], v[90:93]
	ds_read_b128 v[146:149], v128 offset:320
	ds_read_b128 v[150:153], v128 offset:6720
	ds_read_b128 v[168:171], v128 offset:13120
	ds_read_b128 v[172:175], v128 offset:19520
	s_waitcnt lgkmcnt(7)
	v_mfma_f32_16x16x32_bf16 v[78:81], v[34:37], v[176:179], v[78:81]
	s_waitcnt lgkmcnt(6)
	v_mfma_f32_16x16x32_bf16 v[82:85], v[34:37], v[188:191], v[82:85]
	s_waitcnt lgkmcnt(5)
	v_mfma_f32_16x16x32_bf16 v[176:179], v[34:37], v[192:195], v[86:89]
	s_waitcnt lgkmcnt(4)
	v_mfma_f32_16x16x32_bf16 v[188:191], v[34:37], v[196:199], v[90:93]
	s_waitcnt lgkmcnt(3)
	v_mfma_f32_16x16x32_bf16 v[90:93], v[38:41], v[146:149], v[78:81]
	s_waitcnt lgkmcnt(2)
	v_mfma_f32_16x16x32_bf16 v[86:89], v[38:41], v[150:153], v[82:85]
	s_waitcnt lgkmcnt(1)
	v_mfma_f32_16x16x32_bf16 v[82:85], v[38:41], v[168:171], v[176:179]
	s_waitcnt lgkmcnt(0)
	v_mfma_f32_16x16x32_bf16 v[78:81], v[38:41], v[172:175], v[188:191]
	s_mul_i32 s31, s21, 0x4800
	v_add_u32_e32 v154, s31, v141
	v_add_u32_e32 v147, v123, v105
	v_add_u32_e32 v155, 0xc800, v154
	s_nop 3
	v_max3_f32 v146, v90, v86, v82
	v_max3_f32 v148, v91, v87, v83
	v_max3_f32 v149, v92, v88, v84
	v_max3_f32 v150, v93, v89, v85
	v_max_f32_e32 v146, v146, v78
	v_max_f32_e32 v148, v148, v79
	v_max_f32_e32 v149, v149, v80
	v_max_f32_e32 v150, v150, v81
	v_max_f32_dpp v146, v146, v146 row_ror:8 row_mask:0xf bank_mask:0xf
	v_max_f32_dpp v148, v148, v148 row_ror:8 row_mask:0xf bank_mask:0xf
	v_max_f32_dpp v149, v149, v149 row_ror:8 row_mask:0xf bank_mask:0xf
	v_max_f32_dpp v150, v150, v150 row_ror:8 row_mask:0xf bank_mask:0xf
	v_max_f32_dpp v146, v146, v146 row_ror:4 row_mask:0xf bank_mask:0xf
	v_max_f32_dpp v148, v148, v148 row_ror:4 row_mask:0xf bank_mask:0xf
	v_max_f32_dpp v149, v149, v149 row_ror:4 row_mask:0xf bank_mask:0xf
	v_max_f32_dpp v150, v150, v150 row_ror:4 row_mask:0xf bank_mask:0xf
	v_max_f32_dpp v146, v146, v146 row_ror:2 row_mask:0xf bank_mask:0xf
	v_max_f32_dpp v148, v148, v148 row_ror:2 row_mask:0xf bank_mask:0xf
	v_max_f32_dpp v149, v149, v149 row_ror:2 row_mask:0xf bank_mask:0xf
	v_max_f32_dpp v150, v150, v150 row_ror:2 row_mask:0xf bank_mask:0xf
	v_max_f32_dpp v146, v146, v146 row_ror:1 row_mask:0xf bank_mask:0xf
	v_max_f32_dpp v148, v148, v148 row_ror:1 row_mask:0xf bank_mask:0xf
	v_max_f32_dpp v149, v149, v149 row_ror:1 row_mask:0xf bank_mask:0xf
	v_max_f32_dpp v150, v150, v150 row_ror:1 row_mask:0xf bank_mask:0xf
	v_max_f32_e32 v137, v118, v146
	v_max_f32_e32 v136, v119, v148
	v_max_f32_e32 v129, v120, v149
	v_max_f32_e32 v128, v121, v150
	v_sub_f32_e32 v90, v90, v137
	v_sub_f32_e32 v91, v91, v136
	v_sub_f32_e32 v92, v92, v129
	v_sub_f32_e32 v93, v93, v128
	v_sub_f32_e32 v86, v86, v137
	v_sub_f32_e32 v87, v87, v136
	v_sub_f32_e32 v88, v88, v129
	v_sub_f32_e32 v89, v89, v128
	v_sub_f32_e32 v82, v82, v137
	v_sub_f32_e32 v83, v83, v136
	v_sub_f32_e32 v84, v84, v129
	v_sub_f32_e32 v85, v85, v128
	v_sub_f32_e32 v78, v78, v137
	v_sub_f32_e32 v79, v79, v136
	v_sub_f32_e32 v80, v80, v129
	v_sub_f32_e32 v81, v81, v128
	v_exp_f32_e32 v90, v90
	v_exp_f32_e32 v91, v91
	v_exp_f32_e32 v92, v92
	v_exp_f32_e32 v93, v93
	v_exp_f32_e32 v86, v86
	v_exp_f32_e32 v87, v87
	v_exp_f32_e32 v88, v88
	v_exp_f32_e32 v89, v89
	v_exp_f32_e32 v82, v82
	v_exp_f32_e32 v83, v83
	v_exp_f32_e32 v84, v84
	v_exp_f32_e32 v85, v85
	v_exp_f32_e32 v78, v78
	v_exp_f32_e32 v79, v79
	v_exp_f32_e32 v80, v80
	v_exp_f32_e32 v81, v81
	v_cvt_pk_bf16_f32 v151, v90, v86
	ds_write_b16 v147, v151
	ds_write_b16_d16_hi v147, v151 offset:32
	v_cvt_pk_bf16_f32 v152, v82, v78
	ds_write_b16 v147, v152 offset:64
	ds_write_b16_d16_hi v147, v152 offset:96
	v_cvt_pk_bf16_f32 v153, v91, v87
	ds_write_b16 v147, v153 offset:144
	ds_write_b16_d16_hi v147, v153 offset:176
	v_cvt_pk_bf16_f32 v192, v83, v79
	ds_write_b16 v147, v192 offset:208
	ds_write_b16_d16_hi v147, v192 offset:240
	v_cvt_pk_bf16_f32 v151, v92, v88
	ds_write_b16 v147, v151 offset:288
	ds_write_b16_d16_hi v147, v151 offset:320
	v_cvt_pk_bf16_f32 v152, v84, v80
	ds_write_b16 v147, v152 offset:352
	ds_write_b16_d16_hi v147, v152 offset:384
	v_cvt_pk_bf16_f32 v153, v93, v89
	ds_write_b16 v147, v153 offset:432
	ds_write_b16_d16_hi v147, v153 offset:464
	v_cvt_pk_bf16_f32 v192, v85, v81
	ds_write_b16 v147, v192 offset:496
	ds_write_b16_d16_hi v147, v192 offset:528
	s_waitcnt lgkmcnt(0)
; #define LAS __attribute__((address_space(3)))
; __device__ __forceinline__ bf16_t f2bf(float f) { return (bf16_t)(cvt_pk_bf16(f, 0.f) & 0xffffu); }
; #define LDS_FENCE() asm volatile("s_waitcnt lgkmcnt(0)" ::: "memory")
; template <int DQK>
; __device__ __forceinline__ void attn_block(LAS unsigned char* lds, const bf16_t* Qp, const bf16_t* Kp, const bf16_t* VTp, int q_idx0, int kt_lo, int kt_hi,
;                                            int maxdelta, float bslope, int dsh, bf16_t* Op, float* Lp, int head) {
;     ...
;             for (int j = 0; j < 4; ++j) { const float alpha = __builtin_amdgcn_exp2f(m_run[j] - mn[j]); m_run[j] = mn[j];
;                 float psum = 0.f;
; #pragma unroll
;                 for (int n = 0; n < 4; ++n) { const float p = __builtin_amdgcn_exp2f(s[n][j] - mn[j]); psum += p;
;                     *(LAS bf16_t*)(Pw + ((fq * 4 + j) * 72 + n * 16 + fr) * 2) = f2bf(p); }
;                 l_run[j] = l_run[j] * alpha + psum;
; #pragma unroll
;                 for (int d = 0; d < 8; ++d) o[d][j] *= alpha; }
;         }
;         LDS_FENCE();
;         { bf16x8 pf[2], vf[2][4];
;           const LAS unsigned char* vbase_p = Vb + cur * VBYTES + (fr * 72 + fq * 8) * 2;
;           pf[0] = *(const LAS bf16x8*)(Pw + (fr * 72 + fq * 8) * 2); pf[1] = *(const LAS bf16x8*)(Pw + (fr * 72 + 32 + fq * 8) * 2);
; #pragma unroll
;           for (int d4 = 0; d4 < 4; ++d4) vf[0][d4] = *(const LAS bf16x8*)(vbase_p + (d4 * 16 * 72) * 2);
; #pragma unroll
;           for (int gI = 0; gI < 4; ++gI) {
;               if (gI + 1 < 4) {
; #pragma unroll
;                   for (int d4 = 0; d4 < 4; ++d4) vf[(gI + 1) & 1][d4] = *(const LAS bf16x8*)(vbase_p + ((((gI + 1) & 1) * 4 + d4) * 16 * 72 + ((gI + 1) >> 1) * 32) * 2); }
;               __builtin_amdgcn_sched_barrier(0);
; #pragma unroll
;               for (int d4 = 0; d4 < 4; ++d4) o[(gI & 1) * 4 + d4] = __builtin_amdgcn_mfma_f32_16x16x32_bf16(pf[gI >> 1], vf[gI & 1][d4], o[(gI & 1) * 4 + d4], 0, 0, 0);
;               __builtin_amdgcn_sched_barrier(0);
;           } }
;         if (kt + 1 < kt_hi) ATT_STORE(cur ^ 1);
	ds_read_b128 v[146:149], v165
	ds_read_b128 v[150:153], v166 offset:64
	ds_read_b128 v[168:171], v154 offset:51200
	ds_read_b128 v[172:175], v154 offset:53504
	ds_read_b128 v[176:179], v154 offset:55808
	ds_read_b128 v[188:191], v154 offset:58112
	ds_read_b128 v[192:195], v154 offset:60416
	ds_read_b128 v[196:199], v154 offset:62720
	ds_read_b128 v[200:203], v154 offset:65024
	ds_read_b128 v[206:209], v155 offset:16128
	v_sub_f32_e32 v118, v118, v137
	v_sub_f32_e32 v119, v119, v136
	v_sub_f32_e32 v120, v120, v129
	v_sub_f32_e32 v121, v121, v128
	v_exp_f32_e32 v118, v118
	v_exp_f32_e32 v119, v119
	v_exp_f32_e32 v120, v120
	v_exp_f32_e32 v121, v121
	v_pk_mul_f32 v[62:63], v[62:63], v[118:119]
	v_pk_mul_f32 v[58:59], v[58:59], v[118:119]
	v_pk_mul_f32 v[64:65], v[64:65], v[120:121]
	v_pk_mul_f32 v[60:61], v[60:61], v[120:121]
	v_pk_mul_f32 v[52:53], v[52:53], v[120:121]
	v_pk_mul_f32 v[50:51], v[50:51], v[118:119]
	v_pk_mul_f32 v[44:45], v[44:45], v[120:121]
	v_pk_mul_f32 v[42:43], v[42:43], v[118:119]
	v_pk_mul_f32 v[20:21], v[20:21], v[120:121]
	v_pk_mul_f32 v[18:19], v[18:19], v[118:119]
	v_pk_mul_f32 v[12:13], v[12:13], v[120:121]
	v_pk_mul_f32 v[10:11], v[10:11], v[118:119]
	v_pk_mul_f32 v[8:9], v[8:9], v[120:121]
	v_pk_mul_f32 v[6:7], v[6:7], v[118:119]
	v_pk_mul_f32 v[4:5], v[4:5], v[120:121]
	v_pk_mul_f32 v[2:3], v[2:3], v[118:119]
	s_waitcnt lgkmcnt(7)
	v_mfma_f32_16x16x32_bf16 v[62:65], v[146:149], v[168:171], v[62:65]
	s_waitcnt lgkmcnt(6)
	v_mfma_f32_16x16x32_bf16 v[58:61], v[146:149], v[172:175], v[58:61]
	s_waitcnt lgkmcnt(5)
	v_mfma_f32_16x16x32_bf16 v[50:53], v[146:149], v[176:179], v[50:53]
	s_waitcnt lgkmcnt(4)
	v_mfma_f32_16x16x32_bf16 v[42:45], v[146:149], v[188:191], v[42:45]
	ds_read_b128 v[168:171], v154 offset:51264
	ds_read_b128 v[172:175], v154 offset:53568
	ds_read_b128 v[176:179], v154 offset:55872
	ds_read_b128 v[188:191], v154 offset:58176
	s_waitcnt lgkmcnt(7)
	v_mfma_f32_16x16x32_bf16 v[18:21], v[146:149], v[192:195], v[18:21]
	s_waitcnt lgkmcnt(6)
	v_mfma_f32_16x16x32_bf16 v[10:13], v[146:149], v[196:199], v[10:13]
	s_waitcnt lgkmcnt(5)
	v_mfma_f32_16x16x32_bf16 v[6:9], v[146:149], v[200:203], v[6:9]
	s_waitcnt lgkmcnt(4)
	v_mfma_f32_16x16x32_bf16 v[2:5], v[146:149], v[206:209], v[2:5]
	ds_read_b128 v[146:149], v154 offset:60480
	ds_read_b128 v[192:195], v154 offset:62784
	ds_read_b128 v[196:199], v154 offset:65088
	ds_read_b128 v[200:203], v155 offset:16192
	s_waitcnt lgkmcnt(7)
	v_mfma_f32_16x16x32_bf16 v[62:65], v[150:153], v[168:171], v[62:65]
	s_waitcnt lgkmcnt(6)
	v_mfma_f32_16x16x32_bf16 v[58:61], v[150:153], v[172:175], v[58:61]
	s_waitcnt lgkmcnt(5)
	v_mfma_f32_16x16x32_bf16 v[50:53], v[150:153], v[176:179], v[50:53]
	s_waitcnt lgkmcnt(4)
	v_mfma_f32_16x16x32_bf16 v[42:45], v[150:153], v[188:191], v[42:45]
	s_waitcnt lgkmcnt(3)
	v_mfma_f32_16x16x32_bf16 v[18:21], v[150:153], v[146:149], v[18:21]
	s_waitcnt lgkmcnt(2)
	v_mfma_f32_16x16x32_bf16 v[10:13], v[150:153], v[192:195], v[10:13]
	s_waitcnt lgkmcnt(1)
	v_mfma_f32_16x16x32_bf16 v[6:9], v[150:153], v[196:199], v[6:9]
	s_waitcnt lgkmcnt(0)
	v_mfma_f32_16x16x32_bf16 v[2:5], v[150:153], v[200:203], v[2:5]
	s_andn2_b64 vcc, exec, s[46:47]
	s_cbranch_vccnz .LBB0_1220
	s_xor_b32 s21, s21, 1
	s_mul_i32 s31, s21, 0x6400
	s_add_i32 s31, s31, 0
	v_add3_u32 v146, s31, v142, v143
	s_waitcnt vmcnt(4)
	ds_write_b128 v146, v[46:49]
	v_add3_u32 v146, s31, v144, v145
	s_mulk_i32 s21, 0xe400
	s_waitcnt vmcnt(3)
	ds_write_b128 v146, v[54:57]
	v_add3_u32 v146, s31, v156, v157
	s_add_i32 s31, s31, s21
	s_waitcnt vmcnt(2)
	ds_write_b128 v146, v[66:69]
	v_add_u32_e32 v146, s31, v158
	s_waitcnt vmcnt(1)
	ds_write_b128 v146, v[70:73] offset:51200
	v_add_u32_e32 v146, s31, v159
	s_waitcnt vmcnt(0)
	ds_write_b128 v146, v[74:77] offset:51200
